# bundle + P0 residual-stream stores write-through (sc1) so the cooperative grid sync has no dirty L2 lines to flush
# speedup vs baseline: 1.0039x; 1.0015x over previous
.LBB0_18:
	s_waitcnt vmcnt(0)
	v_bfe_u32 v3, v6, 16, 1
	v_add3_u32 v3, v6, v3, s26
	v_bfe_u32 v4, v7, 16, 1
	v_lshrrev_b32_e32 v3, 16, v3
	v_add3_u32 v4, v7, v4, s26
	s_ashr_i32 s13, s12, 31
	v_and_or_b32 v4, v4, s27, v3
	v_bfe_u32 v3, v8, 16, 1
	s_lshl_b64 s[6:7], s[12:13], 12
	v_add3_u32 v3, v8, v3, s26
	v_bfe_u32 v5, v9, 16, 1
	s_add_u32 s18, s80, s6
	v_lshrrev_b32_e32 v3, 16, v3
	v_add3_u32 v5, v9, v5, s26
	s_addc_u32 s19, s81, s7
	v_and_or_b32 v5, v5, s27, v3
	v_cndmask_b32_e64 v3, 0, 1, s[22:23]
	global_store_dwordx2 v47, v[4:5], s[18:19] sc1
	v_cmp_ne_u32_e64 s[6:7], 1, v3
	s_andn2_b64 vcc, exec, s[22:23]
	v_mov_b32_e32 v3, 0
	v_mov_b32_e32 v4, 0
	v_mov_b32_e32 v5, 0
	s_cbranch_vccnz .LBB0_20
	global_load_dwordx4 v[2:5], v34, s[20:21] offset:1024 nt
.LBB0_20:
	s_waitcnt vmcnt(0)
	v_bfe_u32 v10, v2, 16, 1
	v_add3_u32 v10, v2, v10, s26
	v_bfe_u32 v11, v3, 16, 1
	v_lshrrev_b32_e32 v10, 16, v10
	v_add3_u32 v11, v3, v11, s26
	v_and_or_b32 v10, v11, s27, v10
	v_bfe_u32 v11, v4, 16, 1
	v_add3_u32 v11, v4, v11, s26
	v_bfe_u32 v12, v5, 16, 1
	v_lshrrev_b32_e32 v11, 16, v11
	v_add3_u32 v12, v5, v12, s26
	v_and_or_b32 v11, v12, s27, v11
	global_store_dwordx2 v48, v[10:11], s[18:19] sc1
	v_mov_b32_e32 v10, 0
	s_and_b64 vcc, exec, s[6:7]
	v_mov_b32_e32 v14, 0
	v_mov_b32_e32 v15, 0
	v_mov_b32_e32 v16, 0
	v_mov_b32_e32 v17, 0
	s_cbranch_vccnz .LBB0_22
	global_load_dwordx4 v[14:17], v34, s[20:21] offset:2048 nt
.LBB0_22:
	s_waitcnt vmcnt(0)
	v_bfe_u32 v11, v14, 16, 1
	v_add3_u32 v11, v14, v11, s26
	v_bfe_u32 v12, v15, 16, 1
	v_lshrrev_b32_e32 v11, 16, v11
	v_add3_u32 v12, v15, v12, s26
	v_and_or_b32 v12, v12, s27, v11
	v_bfe_u32 v11, v16, 16, 1
	v_add3_u32 v11, v16, v11, s26
	v_bfe_u32 v13, v17, 16, 1
	v_lshrrev_b32_e32 v11, 16, v11
	v_add3_u32 v13, v17, v13, s26
	v_and_or_b32 v13, v13, s27, v11
	global_store_dwordx2 v49, v[12:13], s[18:19] sc1
	s_and_b64 vcc, exec, s[6:7]
	v_mov_b32_e32 v11, 0
	v_mov_b32_e32 v12, 0
	v_mov_b32_e32 v13, 0
	s_cbranch_vccnz .LBB0_24
	global_load_dwordx4 v[10:13], v34, s[20:21] offset:3072 nt
.LBB0_24:
	s_waitcnt vmcnt(0)
	v_bfe_u32 v18, v10, 16, 1
	v_add3_u32 v18, v10, v18, s26
	v_bfe_u32 v19, v11, 16, 1
	v_lshrrev_b32_e32 v18, 16, v18
	v_add3_u32 v19, v11, v19, s26
	v_and_or_b32 v18, v19, s27, v18
	v_bfe_u32 v19, v12, 16, 1
	v_add3_u32 v19, v12, v19, s26
	v_bfe_u32 v20, v13, 16, 1
	v_lshrrev_b32_e32 v19, 16, v19
	v_add3_u32 v20, v13, v20, s26
	v_and_or_b32 v19, v20, s27, v19
	global_store_dwordx2 v50, v[18:19], s[18:19] sc1
	v_mov_b32_e32 v18, 0
	s_and_b64 vcc, exec, s[6:7]
	v_mov_b32_e32 v22, 0
	v_mov_b32_e32 v23, 0
	v_mov_b32_e32 v24, 0
	v_mov_b32_e32 v25, 0
	s_cbranch_vccnz .LBB0_26
	v_lshlrev_b32_e32 v19, 2, v38
	global_load_dwordx4 v[22:25], v19, s[20:21] nt
.LBB0_26:
	s_waitcnt vmcnt(0)
	v_bfe_u32 v19, v22, 16, 1
	v_add3_u32 v19, v22, v19, s26
	v_bfe_u32 v20, v23, 16, 1
	v_lshrrev_b32_e32 v19, 16, v19
	v_add3_u32 v20, v23, v20, s26
	v_and_or_b32 v20, v20, s27, v19
	v_bfe_u32 v19, v24, 16, 1
	v_add3_u32 v19, v24, v19, s26
	v_bfe_u32 v21, v25, 16, 1
	v_lshrrev_b32_e32 v19, 16, v19
	v_add3_u32 v21, v25, v21, s26
	v_and_or_b32 v21, v21, s27, v19
	v_lshlrev_b32_e32 v19, 1, v38
	global_store_dwordx2 v19, v[20:21], s[18:19] sc1
	s_and_b64 vcc, exec, s[6:7]
	v_mov_b32_e32 v19, 0
	v_mov_b32_e32 v20, 0
	v_mov_b32_e32 v21, 0
	s_cbranch_vccnz .LBB0_28
	v_lshlrev_b32_e32 v18, 2, v40
	global_load_dwordx4 v[18:21], v18, s[20:21] nt
.LBB0_28:
	s_waitcnt vmcnt(0)
	v_bfe_u32 v26, v18, 16, 1
	v_add3_u32 v26, v18, v26, s26
	v_bfe_u32 v27, v19, 16, 1
	v_lshrrev_b32_e32 v26, 16, v26
	v_add3_u32 v27, v19, v27, s26
	v_and_or_b32 v26, v27, s27, v26
	v_bfe_u32 v27, v20, 16, 1
	v_add3_u32 v27, v20, v27, s26
	v_bfe_u32 v28, v21, 16, 1
	v_lshrrev_b32_e32 v27, 16, v27
	v_add3_u32 v28, v21, v28, s26
	v_and_or_b32 v27, v28, s27, v27
	v_lshlrev_b32_e32 v28, 1, v40
	global_store_dwordx2 v28, v[26:27], s[18:19] sc1
	v_mov_b32_e32 v26, 0
	s_and_b64 vcc, exec, s[6:7]
	v_mov_b32_e32 v30, 0
	v_mov_b32_e32 v31, 0
	v_mov_b32_e32 v32, 0
	v_mov_b32_e32 v33, 0
	s_cbranch_vccnz .LBB0_30
	v_lshlrev_b32_e32 v27, 2, v42
	global_load_dwordx4 v[30:33], v27, s[20:21] nt
.LBB0_30:
	s_waitcnt vmcnt(0)
	v_bfe_u32 v27, v30, 16, 1
	v_add3_u32 v27, v30, v27, s26
	v_bfe_u32 v28, v31, 16, 1
	v_lshrrev_b32_e32 v27, 16, v27
	v_add3_u32 v28, v31, v28, s26
	v_and_or_b32 v28, v28, s27, v27
	v_bfe_u32 v27, v32, 16, 1
	v_add3_u32 v27, v32, v27, s26
	v_bfe_u32 v29, v33, 16, 1
	v_lshrrev_b32_e32 v27, 16, v27
	v_add3_u32 v29, v33, v29, s26
	v_and_or_b32 v29, v29, s27, v27
	v_lshlrev_b32_e32 v27, 1, v42
	global_store_dwordx2 v27, v[28:29], s[18:19] sc1
	s_and_b64 vcc, exec, s[6:7]
	v_mov_b32_e32 v27, 0
	v_mov_b32_e32 v28, 0
	v_mov_b32_e32 v29, 0
	s_cbranch_vccnz .LBB0_32
	v_lshlrev_b32_e32 v26, 2, v44
	global_load_dwordx4 v[26:29], v26, s[20:21] nt
.LBB0_32:
	v_mul_f32_e32 v3, v3, v3
	v_mul_f32_e32 v7, v7, v7
	v_fmac_f32_e32 v3, v2, v2
	v_mul_f32_e32 v2, v5, v5
	v_fmac_f32_e32 v7, v6, v6
	v_mul_f32_e32 v6, v9, v9
	v_fmac_f32_e32 v2, v4, v4
	v_fmac_f32_e32 v6, v8, v8
	v_add_f32_e32 v2, v3, v2
	v_mul_f32_e32 v3, v15, v15
	v_mul_f32_e32 v4, v17, v17
	v_add_f32_e32 v6, v7, v6
	v_fmac_f32_e32 v3, v14, v14
	v_fmac_f32_e32 v4, v16, v16
	v_add_f32_e32 v2, v6, v2
	v_add_f32_e32 v3, v3, v4
	v_add_f32_e32 v2, v2, v3
	v_mul_f32_e32 v3, v11, v11
	v_mul_f32_e32 v4, v13, v13
	v_fmac_f32_e32 v3, v10, v10
	v_fmac_f32_e32 v4, v12, v12
	v_add_f32_e32 v3, v3, v4
	v_add_f32_e32 v2, v2, v3
	v_mul_f32_e32 v3, v23, v23
	v_mul_f32_e32 v4, v25, v25
	v_fmac_f32_e32 v3, v22, v22
	v_fmac_f32_e32 v4, v24, v24
	v_add_f32_e32 v3, v3, v4
	v_add_f32_e32 v2, v2, v3
	v_mul_f32_e32 v3, v19, v19
	v_mul_f32_e32 v4, v21, v21
	v_fmac_f32_e32 v3, v18, v18
	v_fmac_f32_e32 v4, v20, v20
	v_add_f32_e32 v3, v3, v4
	v_add_f32_e32 v2, v2, v3
	v_mul_f32_e32 v3, v31, v31
	v_mul_f32_e32 v4, v33, v33
	v_fmac_f32_e32 v3, v30, v30
	v_fmac_f32_e32 v4, v32, v32
	v_add_f32_e32 v3, v3, v4
	v_add_f32_e32 v2, v2, v3
	s_waitcnt vmcnt(0)
	v_mul_f32_e32 v3, v27, v27
	v_mul_f32_e32 v4, v29, v29
	v_fmac_f32_e32 v3, v26, v26
	v_fmac_f32_e32 v4, v28, v28
	v_add_f32_e32 v3, v3, v4
	v_add_f32_e32 v2, v2, v3
	ds_bpermute_b32 v3, v1, v2
	v_bfe_u32 v4, v26, 16, 1
	v_add3_u32 v4, v26, v4, s26
	v_bfe_u32 v6, v29, 16, 1
	s_waitcnt lgkmcnt(0)
	v_add_f32_e32 v2, v2, v3
	ds_bpermute_b32 v3, v39, v2
	s_waitcnt lgkmcnt(0)
	v_add_f32_e32 v2, v2, v3
	ds_bpermute_b32 v3, v41, v2
	s_waitcnt lgkmcnt(0)
	v_add_f32_e32 v3, v2, v3
	ds_bpermute_b32 v5, v43, v3
	v_lshrrev_b32_e32 v2, 16, v4
	v_bfe_u32 v4, v27, 16, 1
	v_add3_u32 v4, v27, v4, s26
	v_and_or_b32 v2, v4, s27, v2
	s_waitcnt lgkmcnt(0)
	v_add_f32_e32 v3, v3, v5
	ds_bpermute_b32 v4, v45, v3
	v_bfe_u32 v5, v28, 16, 1
	v_add3_u32 v5, v28, v5, s26
	v_lshrrev_b32_e32 v5, 16, v5
	s_waitcnt lgkmcnt(0)
	v_add_f32_e32 v4, v3, v4
	ds_bpermute_b32 v7, v46, v4
	v_add3_u32 v3, v29, v6, s26
	v_and_or_b32 v3, v3, s27, v5
	v_lshlrev_b32_e32 v5, 1, v44
	global_store_dwordx2 v5, v[2:3], s[18:19] sc1
	s_waitcnt lgkmcnt(0)
	v_add_f32_e32 v2, v4, v7
	s_and_saveexec_b64 s[6:7], s[8:9]
	s_cbranch_execnz .LBB0_34
	s_or_b64 exec, exec, s[6:7]
	s_and_saveexec_b64 s[6:7], s[4:5]
	s_cbranch_execz .LBB0_10
	s_branch .LBB0_35
